# up-GEMM epilogue: dead denormal-range guards around the row-scale v_rsq_f32 removed (argument is mean+1e-6), on top of the packed-add version
# speedup vs baseline: 1.0053x; 1.0053x over previous
; #define PG8_LAS __attribute__((address_space(3)))
; __device__ __forceinline__ float row_up1(float v) { return dpp_mov<0x111>(v); }
;     __device__ __forceinline__ void operator()(f32x4 (&acc)[2][2][4][2], const pg8::Unit& u, int wr, int wc, int fr, int fq) const {
;     ...
;         PG8_LAS unsigned char* wl = WL + (wr * 4 + wc) * 1024;
;         {
;             const int l = fq * 16 + fr, p = l >> 4, bj = (l >> 3) & 1, c4 = (l & 7) * 4;
;             const float* srcp = (p < 3 ? FW + p * NUP : FB) + bj * DFF + u.pn * 128 + wc * 32 + c4;
;             *(PG8_LAS f32x4*)(wl + l * 16) = *(const f32x4*)srcp;
;         }
; #pragma unroll
;         for (int ai = 0; ai < 2; ++ai) {
;             const int tb = u.pm * 256 + ai * 128 + wr * 64 + 4 * fr;
;             float rstd[4];
; #pragma unroll
;             for (int m = 0; m < 4; ++m) { const f32x4 sv = *(const f32x4*)(SS + (size_t)(tb + m) * 16 + 4 * fq); float s = (sv[0] + sv[1]) + (sv[2] + sv[3]); s += __shfl_xor(s, 16); s += __shfl_xor(s, 32);
;                 rstd[m] = rsqrtf(s * (1.0f / 1024.0f) + EPS); }
;             u32x2 pk[2][4];
; #pragma unroll
;             for (int n = 0; n < 2; ++n) {
;                 f32x4 g[4];
;                 {   const PG8_LAS unsigned char* wq = wl + (8 * fq + 4 * n) * 4;
;                     const f32x4 w0 = *(const PG8_LAS f32x4*)(wq), w1 = *(const PG8_LAS f32x4*)(wq + 256), w2 = *(const PG8_LAS f32x4*)(wq + 512), bb = *(const PG8_LAS f32x4*)(wq + 768);
;                     const f32x4 x0 = acc[ai][0][0][n] * rstd[0], x1 = acc[ai][0][1][n] * rstd[1], x2 = acc[ai][0][2][n] * rstd[2], x3 = acc[ai][0][3][n] * rstd[3];
;                     acc[ai][0][0][n] = x0; acc[ai][0][1][n] = x1; acc[ai][0][2][n] = x2; acc[ai][0][3][n] = x3;
;                     f32x4 p1, p2;
; #pragma unroll
;                     for (int c = 0; c < 4; ++c) { p1[c] = row_up1(x3[c]); p2[c] = row_up1(x2[c]); }
;                     g[0] = bb + w2 * x0 + w1 * p1 + w0 * p2; g[1] = bb + w2 * x1 + w1 * x0 + w0 * p1;
;                     g[2] = bb + w2 * x2 + w1 * x1 + w0 * x0; g[3] = bb + w2 * x3 + w1 * x2 + w0 * x1;
; #pragma unroll
;                     for (int m = 0; m < 4; ++m)
; #pragma unroll
;                         for (int c = 0; c < 4; ++c) g[m][c] = siluf_(g[m][c]);
.LBB0_748:
	v_lshl_add_u32 v148, s34, 8, v187
	v_ashrrev_i32_e32 v149, 31, v148
	v_lshlrev_b64 v[150:151], 6, v[148:149]
	v_lshl_add_u64 v[154:155], v[138:139], 0, v[150:151]
	v_or_b32_e32 v150, 1, v148
	v_ashrrev_i32_e32 v151, 31, v150
	v_lshlrev_b64 v[156:157], 6, v[150:151]
	v_lshl_add_u64 v[156:157], v[138:139], 0, v[156:157]
	global_load_dwordx4 v[160:163], v[154:155], off
	global_load_dwordx4 v[164:167], v[156:157], off
	v_or_b32_e32 v154, 2, v148
	v_ashrrev_i32_e32 v155, 31, v154
	v_lshlrev_b64 v[156:157], 6, v[154:155]
	v_lshl_add_u64 v[156:157], v[138:139], 0, v[156:157]
	global_load_dwordx4 v[172:175], v[156:157], off
	v_or_b32_e32 v156, 3, v148
	v_ashrrev_i32_e32 v157, 31, v156
	v_lshlrev_b64 v[158:159], 6, v[156:157]
	v_lshl_add_u64 v[158:159], v[138:139], 0, v[158:159]
	global_load_dwordx4 v[176:179], v[158:159], off
	s_lshl_b32 s8, s66, 7
	s_ashr_i32 s9, s8, 31
	v_lshl_add_u64 v[158:159], s[8:9], 2, v[136:137]
	global_load_dwordx4 v[180:183], v[158:159], off
	v_and_b32_e32 v151, 64, v194
	v_xor_b32_e32 v149, 16, v194
	v_add_u32_e32 v151, 64, v151
	v_cmp_lt_i32_e32 vcc, v149, v151
	v_xor_b32_e32 v155, 32, v194
	v_mov_b64_e32 v[184:185], s[38:39]
	v_cndmask_b32_e32 v149, v194, v149, vcc
	v_lshlrev_b32_e32 v149, 2, v149
	v_cmp_lt_i32_e32 vcc, v155, v151
	v_or_b32_e32 v158, s8, v186
	v_ashrrev_i32_e32 v159, 31, v158
	v_cndmask_b32_e32 v151, v194, v155, vcc
	v_lshlrev_b32_e32 v151, 2, v151
	s_waitcnt vmcnt(0)
	v_mov_b32_e32 v196, v161
	v_mov_b32_e32 v197, v162
	v_mov_b32_e32 v161, v163
	v_mov_b32_e32 v162, v165
	v_mov_b32_e32 v163, v166
	v_mov_b32_e32 v165, v167
	v_mov_b32_e32 v166, v173
	v_mov_b32_e32 v167, v174
	v_mov_b32_e32 v173, v175
	v_pk_add_f32 v[160:161], v[196:197], v[160:161]
	v_pk_add_f32 v[162:163], v[162:163], v[164:165]
	v_mov_b32_e32 v174, v177
	v_mov_b32_e32 v175, v178
	v_mov_b32_e32 v177, v179
	v_pk_add_f32 v[166:167], v[166:167], v[172:173]
	v_pk_add_f32 v[172:173], v[174:175], v[176:177]
	v_mov_b32_e32 v165, v160
	v_mov_b32_e32 v164, v162
	v_mov_b32_e32 v160, v163
	v_mov_b32_e32 v162, v172
	v_mov_b32_e32 v163, v166
	v_mov_b32_e32 v166, v173
	v_pk_add_f32 v[160:161], v[164:165], v[160:161]
	v_pk_add_f32 v[162:163], v[162:163], v[166:167]
	ds_bpermute_b32 v165, v149, v161
	ds_bpermute_b32 v164, v149, v160
	ds_bpermute_b32 v167, v149, v163
	ds_bpermute_b32 v166, v149, v162
	v_mul_f32_e32 v180, v239, v180
	v_mul_f32_e32 v181, v239, v181
	v_mul_f32_e32 v182, v239, v182
	v_mul_f32_e32 v183, v239, v183
	ds_write_b128 v193, v[180:183]
	s_waitcnt lgkmcnt(3)
	v_pk_add_f32 v[172:173], v[160:161], v[164:165]
	ds_bpermute_b32 v197, v151, v173
	s_waitcnt lgkmcnt(2)
	v_pk_add_f32 v[174:175], v[162:163], v[166:167]
	ds_bpermute_b32 v196, v151, v172
	ds_bpermute_b32 v199, v151, v175
	ds_bpermute_b32 v198, v151, v174
	ds_read_b128 v[160:163], v195
	ds_read_b128 v[164:167], v195 offset:256
	ds_read_b128 v[176:179], v195 offset:512
	ds_read_b128 v[180:183], v195 offset:768
	s_waitcnt lgkmcnt(6)
	v_pk_add_f32 v[172:173], v[172:173], v[196:197]
	s_nop 0
	v_pk_fma_f32 v[172:173], v[172:173], s[24:25], v[184:185] op_sel_hi:[1,0,0]
	s_waitcnt lgkmcnt(4)
	v_pk_add_f32 v[174:175], v[174:175], v[198:199]
	v_pk_fma_f32 v[174:175], v[174:175], s[24:25], v[184:185] op_sel_hi:[1,0,0]
	v_rsq_f32_e32 v155, v173
	v_rsq_f32_e32 v168, v175
	v_rsq_f32_e32 v173, v174
	v_rsq_f32_e32 v157, v172
	v_mov_b32_e32 v174, v155
	v_mov_b32_e32 v170, v168
	v_mov_b32_e32 v168, v173
	v_pk_mul_f32 v[124:125], v[124:125], v[174:175] op_sel_hi:[1,0]
	v_pk_mul_f32 v[112:113], v[112:113], v[168:169] op_sel_hi:[1,0]
	v_pk_mul_f32 v[116:117], v[116:117], v[170:171] op_sel_hi:[1,0]
	s_waitcnt lgkmcnt(0)
	v_pk_fma_f32 v[204:205], v[176:177], v[124:125], v[180:181]
	v_mov_b32_dpp v184, v112 row_shr:1 row_mask:0xf bank_mask:0xf bound_ctrl:1
	v_mov_b32_dpp v185, v113 row_shr:1 row_mask:0xf bank_mask:0xf bound_ctrl:1
	v_mov_b32_dpp v196, v116 row_shr:1 row_mask:0xf bank_mask:0xf bound_ctrl:1
	v_mov_b32_dpp v197, v117 row_shr:1 row_mask:0xf bank_mask:0xf bound_ctrl:1
	v_pk_fma_f32 v[204:205], v[164:165], v[184:185], v[204:205]
	v_pk_fma_f32 v[196:197], v[160:161], v[196:197], v[204:205]
	v_mov_b32_e32 v172, v157
	v_pk_mul_f32 v[126:127], v[126:127], v[174:175] op_sel_hi:[1,0]
	v_pk_mul_f32 v[120:121], v[120:121], v[172:173] op_sel_hi:[1,0]
	v_pk_mul_f32 v[114:115], v[114:115], v[168:169] op_sel_hi:[1,0]
	v_exp_f32_e32 v240, v196
	v_pk_mul_f32 v[118:119], v[118:119], v[170:171] op_sel_hi:[1,0]
	v_mov_b32_dpp v198, v114 row_shr:1 row_mask:0xf bank_mask:0xf bound_ctrl:1
	v_mov_b32_dpp v199, v115 row_shr:1 row_mask:0xf bank_mask:0xf bound_ctrl:1
	v_pk_fma_f32 v[202:203], v[178:179], v[126:127], v[182:183]
	v_pk_fma_f32 v[204:205], v[176:177], v[120:121], v[180:181]
	v_exp_f32_e32 v241, v197
	v_pk_mul_f32 v[122:123], v[122:123], v[172:173] op_sel_hi:[1,0]
	v_mov_b32_dpp v200, v118 row_shr:1 row_mask:0xf bank_mask:0xf bound_ctrl:1
	v_mov_b32_dpp v201, v119 row_shr:1 row_mask:0xf bank_mask:0xf bound_ctrl:1
	v_pk_fma_f32 v[202:203], v[166:167], v[198:199], v[202:203]
	v_pk_fma_f32 v[204:205], v[164:165], v[124:125], v[204:205]
	v_pk_fma_f32 v[200:201], v[162:163], v[200:201], v[202:203]
	v_pk_fma_f32 v[202:203], v[178:179], v[122:123], v[182:183]
	v_pk_fma_f32 v[184:185], v[160:161], v[184:185], v[204:205]
	v_pk_fma_f32 v[204:205], v[176:177], v[116:117], v[180:181]
	v_pk_fma_f32 v[176:177], v[176:177], v[112:113], v[180:181]
	v_pk_fma_f32 v[202:203], v[166:167], v[126:127], v[202:203]
	v_pk_fma_f32 v[204:205], v[164:165], v[120:121], v[204:205]
	v_pk_fma_f32 v[164:165], v[164:165], v[116:117], v[176:177]
	v_pk_fma_f32 v[198:199], v[162:163], v[198:199], v[202:203]
; #define PG8_LAS __attribute__((address_space(3)))
; __device__ __forceinline__ unsigned pk2(float a, float b) { return pg8::cvt_pk_bf16(a, b); }
; __device__ __forceinline__ float row_up1(float v) { return dpp_mov<0x111>(v); }
; __device__ __forceinline__ float siluf_(float x) { return x * __builtin_amdgcn_rcpf(1.0f + __builtin_amdgcn_exp2f(x * -1.4426950408889634f)); }
;     __device__ __forceinline__ void operator()(f32x4 (&acc)[2][2][4][2], const pg8::Unit& u, int wr, int wc, int fr, int fq) const {
;     ...
;                     g[0] = bb + w2 * x0 + w1 * p1 + w0 * p2; g[1] = bb + w2 * x1 + w1 * x0 + w0 * p1;
;                     g[2] = bb + w2 * x2 + w1 * x1 + w0 * x0; g[3] = bb + w2 * x3 + w1 * x2 + w0 * x1;
; #pragma unroll
;                     for (int m = 0; m < 4; ++m)
; #pragma unroll
;                         for (int c = 0; c < 4; ++c) g[m][c] = siluf_(g[m][c]);
;                 }
;                 __builtin_amdgcn_sched_barrier(0);
;                 {   const PG8_LAS unsigned char* wq = wl + 128 + (8 * fq + 4 * n) * 4;
;                     const f32x4 w0 = *(const PG8_LAS f32x4*)(wq), w1 = *(const PG8_LAS f32x4*)(wq + 256), w2 = *(const PG8_LAS f32x4*)(wq + 512), bb = *(const PG8_LAS f32x4*)(wq + 768);
;                     const f32x4 x0 = acc[ai][1][0][n] * rstd[0], x1 = acc[ai][1][1][n] * rstd[1], x2 = acc[ai][1][2][n] * rstd[2], x3 = acc[ai][1][3][n] * rstd[3];
;                     acc[ai][1][0][n] = x0; acc[ai][1][1][n] = x1; acc[ai][1][2][n] = x2; acc[ai][1][3][n] = x3;
;                     f32x4 p1, p2;
; #pragma unroll
;                     for (int c = 0; c < 4; ++c) { p1[c] = row_up1(x3[c]); p2[c] = row_up1(x2[c]); }
;                     g[0] *= bb + w2 * x0 + w1 * p1 + w0 * p2; g[1] *= bb + w2 * x1 + w1 * x0 + w0 * p1;
;                     g[2] *= bb + w2 * x2 + w1 * x1 + w0 * x0; g[3] *= bb + w2 * x3 + w1 * x2 + w0 * x1;
;                 }
; #pragma unroll
;                 for (int m = 0; m < 4; ++m) { pk[n][m].x = pk2(g[m][0], g[m][1]); pk[n][m].y = pk2(g[m][2], g[m][3]); }
	v_pk_fma_f32 v[202:203], v[178:179], v[118:119], v[182:183]
	v_pk_fma_f32 v[204:205], v[160:161], v[124:125], v[204:205]
	v_pk_fma_f32 v[178:179], v[178:179], v[114:115], v[182:183]
	v_pk_fma_f32 v[214:215], v[160:161], v[120:121], v[164:165]
	v_pk_add_f32 v[240:241], v[240:241], v[250:251]
	v_rcp_f32_e32 v160, v240
	v_pk_fma_f32 v[202:203], v[166:167], v[122:123], v[202:203]
	v_pk_fma_f32 v[166:167], v[166:167], v[118:119], v[178:179]
	v_exp_f32_e32 v242, v200
	v_pk_fma_f32 v[202:203], v[162:163], v[126:127], v[202:203]
	v_pk_fma_f32 v[212:213], v[162:163], v[122:123], v[166:167]
	v_exp_f32_e32 v243, v201
	v_rcp_f32_e32 v161, v241
	v_pk_add_f32 v[242:243], v[242:243], v[250:251]
	v_rcp_f32_e32 v162, v242
	v_rcp_f32_e32 v163, v243
	v_exp_f32_e32 v244, v184
	v_exp_f32_e32 v245, v185
	v_pk_mul_f32 v[216:217], v[196:197], v[160:161]
	v_pk_add_f32 v[244:245], v[244:245], v[250:251]
	v_rcp_f32_e32 v160, v244
	v_exp_f32_e32 v246, v198
	v_pk_mul_f32 v[218:219], v[200:201], v[162:163]
	v_exp_f32_e32 v247, v199
	v_rcp_f32_e32 v161, v245
	v_pk_add_f32 v[246:247], v[246:247], v[250:251]
	v_rcp_f32_e32 v162, v246
	v_rcp_f32_e32 v163, v247
	v_exp_f32_e32 v248, v204
	v_exp_f32_e32 v249, v205
	v_pk_mul_f32 v[184:185], v[184:185], v[160:161]
	v_pk_add_f32 v[248:249], v[248:249], v[250:251]
	v_rcp_f32_e32 v160, v248
	v_exp_f32_e32 v240, v202
	v_exp_f32_e32 v241, v203
	v_rcp_f32_e32 v161, v249
	v_pk_add_f32 v[240:241], v[240:241], v[250:251]
	v_rcp_f32_e32 v164, v240
	v_exp_f32_e32 v242, v214
	v_exp_f32_e32 v243, v215
	v_rcp_f32_e32 v165, v241
	v_pk_add_f32 v[242:243], v[242:243], v[250:251]
	v_rcp_f32_e32 v220, v242
	v_exp_f32_e32 v244, v212
	v_exp_f32_e32 v245, v213
	v_rcp_f32_e32 v221, v243
	v_pk_add_f32 v[244:245], v[244:245], v[250:251]
	v_rcp_f32_e32 v222, v244
	v_rcp_f32_e32 v223, v245
	v_pk_mul_f32 v[224:225], v[198:199], v[162:163]
	v_pk_mul_f32 v[226:227], v[204:205], v[160:161]
	v_pk_mul_f32 v[228:229], v[202:203], v[164:165]
	ds_read_b128 v[196:199], v195 offset:128
	ds_read_b128 v[200:203], v195 offset:384
	ds_read_b128 v[204:207], v195 offset:640
	ds_read_b128 v[208:211], v195 offset:896
	v_pk_mul_f32 v[176:177], v[108:109], v[174:175] op_sel_hi:[1,0]
	v_pk_mul_f32 v[164:165], v[96:97], v[168:169] op_sel_hi:[1,0]
	v_pk_mul_f32 v[180:181], v[100:101], v[170:171] op_sel_hi:[1,0]
	v_pk_mul_f32 v[160:161], v[104:105], v[172:173] op_sel_hi:[1,0]
	v_mov_b32_dpp v96, v164 row_shr:1 row_mask:0xf bank_mask:0xf bound_ctrl:1
	v_mov_b32_dpp v97, v165 row_shr:1 row_mask:0xf bank_mask:0xf bound_ctrl:1
	s_waitcnt lgkmcnt(0)
	v_pk_fma_f32 v[108:109], v[176:177], v[204:205], v[208:209]
	v_pk_mul_f32 v[166:167], v[98:99], v[168:169] op_sel_hi:[1,0]
	v_mov_b32_dpp v98, v180 row_shr:1 row_mask:0xf bank_mask:0xf bound_ctrl:1
	v_mov_b32_dpp v99, v181 row_shr:1 row_mask:0xf bank_mask:0xf bound_ctrl:1
	v_pk_fma_f32 v[108:109], v[200:201], v[96:97], v[108:109]
	v_pk_mul_f32 v[178:179], v[110:111], v[174:175] op_sel_hi:[1,0]
	v_pk_fma_f32 v[98:99], v[196:197], v[98:99], v[108:109]
	v_pk_fma_f32 v[108:109], v[160:161], v[204:205], v[208:209]
	v_pk_mul_f32 v[182:183], v[102:103], v[170:171] op_sel_hi:[1,0]
	v_mov_b32_dpp v100, v166 row_shr:1 row_mask:0xf bank_mask:0xf bound_ctrl:1
	v_mov_b32_dpp v101, v167 row_shr:1 row_mask:0xf bank_mask:0xf bound_ctrl:1
	v_pk_fma_f32 v[110:111], v[178:179], v[206:207], v[210:211]
	v_pk_fma_f32 v[108:109], v[176:177], v[200:201], v[108:109]
	v_pk_mul_f32 v[162:163], v[106:107], v[172:173] op_sel_hi:[1,0]
	v_mov_b32_dpp v102, v182 row_shr:1 row_mask:0xf bank_mask:0xf bound_ctrl:1
	v_mov_b32_dpp v103, v183 row_shr:1 row_mask:0xf bank_mask:0xf bound_ctrl:1
	v_pk_fma_f32 v[110:111], v[202:203], v[100:101], v[110:111]
	v_pk_fma_f32 v[96:97], v[196:197], v[96:97], v[108:109]
	v_pk_fma_f32 v[108:109], v[180:181], v[204:205], v[208:209]
	v_pk_fma_f32 v[102:103], v[198:199], v[102:103], v[110:111]
	v_pk_fma_f32 v[110:111], v[162:163], v[206:207], v[210:211]
	v_pk_fma_f32 v[108:109], v[160:161], v[200:201], v[108:109]
	v_pk_fma_f32 v[110:111], v[178:179], v[202:203], v[110:111]
	v_pk_fma_f32 v[108:109], v[176:177], v[196:197], v[108:109]
	v_pk_fma_f32 v[100:101], v[198:199], v[100:101], v[110:111]
	v_pk_mul_f32 v[96:97], v[184:185], v[96:97]
	v_pk_fma_f32 v[110:111], v[182:183], v[206:207], v[210:211]
	v_pk_mul_f32 v[184:185], v[108:109], v[226:227]
	v_pk_fma_f32 v[108:109], v[164:165], v[204:205], v[208:209]
	v_pk_fma_f32 v[204:205], v[166:167], v[206:207], v[210:211]
	v_pk_fma_f32 v[110:111], v[162:163], v[202:203], v[110:111]
	v_pk_fma_f32 v[202:203], v[182:183], v[202:203], v[204:205]
	v_pk_fma_f32 v[108:109], v[180:181], v[200:201], v[108:109]
	v_pk_mul_f32 v[106:107], v[212:213], v[222:223]
	v_pk_fma_f32 v[110:111], v[178:179], v[198:199], v[110:111]
	v_pk_fma_f32 v[108:109], v[160:161], v[196:197], v[108:109]
	v_pk_fma_f32 v[196:197], v[162:163], v[198:199], v[202:203]
	v_pk_mul_f32 v[104:105], v[214:215], v[220:221]
	v_pk_mul_f32 v[102:103], v[218:219], v[102:103]
	v_pk_mul_f32 v[98:99], v[216:217], v[98:99]
	v_pk_mul_f32 v[100:101], v[224:225], v[100:101]
	v_pk_mul_f32 v[110:111], v[110:111], v[228:229]
	v_pk_mul_f32 v[106:107], v[196:197], v[106:107]
	v_pk_mul_f32 v[196:197], v[108:109], v[104:105]
	v_cvt_pk_bf16_f32 v108, v98, v99
	v_cvt_pk_bf16_f32 v109, v102, v103
	v_cvt_pk_bf16_f32 v104, v96, v97
	v_cvt_pk_bf16_f32 v105, v100, v101
	v_cvt_pk_bf16_f32 v100, v184, v185
	v_cvt_pk_bf16_f32 v101, v110, v111
	s_nop 0
	v_cvt_pk_bf16_f32 v96, v196, v197
	v_cvt_pk_bf16_f32 v97, v106, v107
	ds_read_b128 v[196:199], v195 offset:16
	ds_read_b128 v[200:203], v195 offset:272
	ds_read_b128 v[204:207], v195 offset:528
	ds_read_b128 v[208:211], v195 offset:784
	v_pk_mul_f32 v[92:93], v[92:93], v[174:175] op_sel_hi:[1,0]
	v_pk_mul_f32 v[84:85], v[84:85], v[168:169] op_sel_hi:[1,0]
	v_pk_mul_f32 v[88:89], v[88:89], v[170:171] op_sel_hi:[1,0]
	v_pk_mul_f32 v[80:81], v[80:81], v[172:173] op_sel_hi:[1,0]
	v_mov_b32_dpp v98, v84 row_shr:1 row_mask:0xf bank_mask:0xf bound_ctrl:1
	v_mov_b32_dpp v99, v85 row_shr:1 row_mask:0xf bank_mask:0xf bound_ctrl:1
	s_waitcnt lgkmcnt(0)
; #define PG8_LAS __attribute__((address_space(3)))
; __device__ __forceinline__ float row_up1(float v) { return dpp_mov<0x111>(v); }
; __device__ __forceinline__ float siluf_(float x) { return x * __builtin_amdgcn_rcpf(1.0f + __builtin_amdgcn_exp2f(x * -1.4426950408889634f)); }
;     __device__ __forceinline__ void operator()(f32x4 (&acc)[2][2][4][2], const pg8::Unit& u, int wr, int wc, int fr, int fq) const {
;     ...
;                     g[0] = bb + w2 * x0 + w1 * p1 + w0 * p2; g[1] = bb + w2 * x1 + w1 * x0 + w0 * p1;
;                     g[2] = bb + w2 * x2 + w1 * x1 + w0 * x0; g[3] = bb + w2 * x3 + w1 * x2 + w0 * x1;
; #pragma unroll
;                     for (int m = 0; m < 4; ++m)
; #pragma unroll
;                         for (int c = 0; c < 4; ++c) g[m][c] = siluf_(g[m][c]);
;                 }
;                 __builtin_amdgcn_sched_barrier(0);
;                 {   const PG8_LAS unsigned char* wq = wl + 128 + (8 * fq + 4 * n) * 4;
;                     const f32x4 w0 = *(const PG8_LAS f32x4*)(wq), w1 = *(const PG8_LAS f32x4*)(wq + 256), w2 = *(const PG8_LAS f32x4*)(wq + 512), bb = *(const PG8_LAS f32x4*)(wq + 768);
;                     const f32x4 x0 = acc[ai][1][0][n] * rstd[0], x1 = acc[ai][1][1][n] * rstd[1], x2 = acc[ai][1][2][n] * rstd[2], x3 = acc[ai][1][3][n] * rstd[3];
;                     acc[ai][1][0][n] = x0; acc[ai][1][1][n] = x1; acc[ai][1][2][n] = x2; acc[ai][1][3][n] = x3;
;                     f32x4 p1, p2;
; #pragma unroll
;                     for (int c = 0; c < 4; ++c) { p1[c] = row_up1(x3[c]); p2[c] = row_up1(x2[c]); }
;                     g[0] *= bb + w2 * x0 + w1 * p1 + w0 * p2; g[1] *= bb + w2 * x1 + w1 * x0 + w0 * p1;
	v_pk_fma_f32 v[212:213], v[92:93], v[204:205], v[208:209]
	v_mov_b32_dpp v102, v88 row_shr:1 row_mask:0xf bank_mask:0xf bound_ctrl:1
	v_mov_b32_dpp v103, v89 row_shr:1 row_mask:0xf bank_mask:0xf bound_ctrl:1
	v_pk_fma_f32 v[212:213], v[200:201], v[98:99], v[212:213]
	v_pk_mul_f32 v[94:95], v[94:95], v[174:175] op_sel_hi:[1,0]
	v_pk_fma_f32 v[102:103], v[196:197], v[102:103], v[212:213]
	v_pk_mul_f32 v[86:87], v[86:87], v[168:169] op_sel_hi:[1,0]
	v_exp_f32_e32 v246, v102
	v_pk_fma_f32 v[212:213], v[80:81], v[204:205], v[208:209]
	v_exp_f32_e32 v247, v103
	v_pk_mul_f32 v[90:91], v[90:91], v[170:171] op_sel_hi:[1,0]
	v_mov_b32_dpp v106, v86 row_shr:1 row_mask:0xf bank_mask:0xf bound_ctrl:1
	v_mov_b32_dpp v107, v87 row_shr:1 row_mask:0xf bank_mask:0xf bound_ctrl:1
	v_pk_fma_f32 v[184:185], v[94:95], v[206:207], v[210:211]
	v_pk_fma_f32 v[212:213], v[92:93], v[200:201], v[212:213]
	v_mov_b32_dpp v110, v90 row_shr:1 row_mask:0xf bank_mask:0xf bound_ctrl:1
	v_mov_b32_dpp v111, v91 row_shr:1 row_mask:0xf bank_mask:0xf bound_ctrl:1
	v_pk_fma_f32 v[184:185], v[202:203], v[106:107], v[184:185]
	v_pk_fma_f32 v[98:99], v[196:197], v[98:99], v[212:213]
	v_pk_fma_f32 v[212:213], v[88:89], v[204:205], v[208:209]
	v_pk_fma_f32 v[204:205], v[84:85], v[204:205], v[208:209]
	v_pk_fma_f32 v[110:111], v[198:199], v[110:111], v[184:185]
	v_pk_fma_f32 v[212:213], v[80:81], v[200:201], v[212:213]
	v_pk_fma_f32 v[200:201], v[88:89], v[200:201], v[204:205]
	v_pk_fma_f32 v[212:213], v[92:93], v[196:197], v[212:213]
	v_pk_fma_f32 v[216:217], v[80:81], v[196:197], v[200:201]
	v_pk_add_f32 v[246:247], v[246:247], v[250:251]
	v_rcp_f32_e32 v196, v246
	v_pk_mul_f32 v[82:83], v[82:83], v[172:173] op_sel_hi:[1,0]
	v_exp_f32_e32 v248, v110
	v_pk_fma_f32 v[184:185], v[82:83], v[206:207], v[210:211]
	v_exp_f32_e32 v249, v111
	v_pk_fma_f32 v[184:185], v[94:95], v[202:203], v[184:185]
	v_rcp_f32_e32 v197, v247
	v_pk_fma_f32 v[106:107], v[198:199], v[106:107], v[184:185]
	v_pk_fma_f32 v[184:185], v[90:91], v[206:207], v[210:211]
	v_pk_fma_f32 v[206:207], v[86:87], v[206:207], v[210:211]
	v_pk_fma_f32 v[184:185], v[82:83], v[202:203], v[184:185]
	v_pk_fma_f32 v[202:203], v[90:91], v[202:203], v[206:207]
	v_pk_fma_f32 v[184:185], v[94:95], v[198:199], v[184:185]
	v_pk_fma_f32 v[214:215], v[82:83], v[198:199], v[202:203]
	v_pk_add_f32 v[248:249], v[248:249], v[250:251]
	v_rcp_f32_e32 v198, v248
	v_rcp_f32_e32 v199, v249
	v_exp_f32_e32 v240, v98
	v_exp_f32_e32 v241, v99
	v_pk_mul_f32 v[102:103], v[102:103], v[196:197]
	v_pk_add_f32 v[240:241], v[240:241], v[250:251]
	v_rcp_f32_e32 v196, v240
	v_exp_f32_e32 v242, v106
	v_exp_f32_e32 v243, v107
	v_rcp_f32_e32 v197, v241
	v_pk_mul_f32 v[110:111], v[110:111], v[198:199]
	v_pk_add_f32 v[242:243], v[242:243], v[250:251]
	v_rcp_f32_e32 v198, v242
	v_rcp_f32_e32 v199, v243
	v_exp_f32_e32 v244, v212
	v_exp_f32_e32 v245, v213
	v_pk_mul_f32 v[98:99], v[98:99], v[196:197]
	v_pk_add_f32 v[244:245], v[244:245], v[250:251]
	v_rcp_f32_e32 v196, v244
	v_exp_f32_e32 v246, v184
	v_exp_f32_e32 v247, v185
	v_rcp_f32_e32 v197, v245
	v_pk_add_f32 v[246:247], v[246:247], v[250:251]
	v_rcp_f32_e32 v200, v246
	v_exp_f32_e32 v248, v216
	v_exp_f32_e32 v249, v217
	v_rcp_f32_e32 v201, v247
	v_pk_add_f32 v[248:249], v[248:249], v[250:251]
	v_rcp_f32_e32 v218, v248
	v_exp_f32_e32 v240, v214
	v_exp_f32_e32 v241, v215
	v_rcp_f32_e32 v219, v249
	v_pk_add_f32 v[240:241], v[240:241], v[250:251]
	v_rcp_f32_e32 v220, v240
	v_pk_mul_f32 v[106:107], v[106:107], v[198:199]
	v_rcp_f32_e32 v221, v241
	v_pk_mul_f32 v[212:213], v[212:213], v[196:197]
	v_pk_mul_f32 v[222:223], v[184:185], v[200:201]
	ds_read_b128 v[196:199], v195 offset:144
	ds_read_b128 v[200:203], v195 offset:400
	ds_read_b128 v[204:207], v195 offset:656
	ds_read_b128 v[208:211], v195 offset:912
	v_pk_mul_f32 v[184:185], v[66:67], v[174:175] op_sel_hi:[1,0]
	v_pk_mul_f32 v[174:175], v[64:65], v[174:175] op_sel_hi:[1,0]
	v_pk_mul_f32 v[66:67], v[68:69], v[172:173] op_sel_hi:[1,0]
	v_pk_mul_f32 v[68:69], v[76:77], v[168:169] op_sel_hi:[1,0]
	v_pk_mul_f32 v[70:71], v[70:71], v[172:173] op_sel_hi:[1,0]
	v_pk_mul_f32 v[172:173], v[74:75], v[170:171] op_sel_hi:[1,0]
	v_pk_mul_f32 v[74:75], v[72:73], v[170:171] op_sel_hi:[1,0]
	v_mov_b32_dpp v64, v68 row_shr:1 row_mask:0xf bank_mask:0xf bound_ctrl:1
	v_mov_b32_dpp v65, v69 row_shr:1 row_mask:0xf bank_mask:0xf bound_ctrl:1
	v_pk_mul_f32 v[216:217], v[216:217], v[218:219]
	s_waitcnt lgkmcnt(0)
; __device__ __forceinline__ unsigned pk2(float a, float b) { return pg8::cvt_pk_bf16(a, b); }
;     __device__ __forceinline__ void operator()(f32x4 (&acc)[2][2][4][2], const pg8::Unit& u, int wr, int wc, int fr, int fq) const {
;     ...
;                     g[0] *= bb + w2 * x0 + w1 * p1 + w0 * p2; g[1] *= bb + w2 * x1 + w1 * x0 + w0 * p1;
;                     g[2] *= bb + w2 * x2 + w1 * x1 + w0 * x0; g[3] *= bb + w2 * x3 + w1 * x2 + w0 * x1;
;                 }
; #pragma unroll
;                 for (int m = 0; m < 4; ++m) { pk[n][m].x = pk2(g[m][0], g[m][1]); pk[n][m].y = pk2(g[m][2], g[m][3]); }
;                 __builtin_amdgcn_sched_barrier(0);
;             }
; #pragma unroll
;             for (int m = 0; m < 4; ++m) if (fr != 0 || m >= 2) {
;                 u32x4 w; w.x = pk[0][m].x; w.y = pk[0][m].y; w.z = pk[1][m].x; w.w = pk[1][m].y;
;                 *(u32x4*)(ACT + (size_t)(tb + m) * DFF + colj) = w; }
	v_pk_fma_f32 v[218:219], v[174:175], v[204:205], v[208:209]
	v_pk_mul_f32 v[72:73], v[78:79], v[168:169] op_sel_hi:[1,0]
	v_mov_b32_dpp v76, v74 row_shr:1 row_mask:0xf bank_mask:0xf bound_ctrl:1
	v_mov_b32_dpp v77, v75 row_shr:1 row_mask:0xf bank_mask:0xf bound_ctrl:1
	v_pk_fma_f32 v[218:219], v[200:201], v[64:65], v[218:219]
	v_mov_b32_dpp v78, v72 row_shr:1 row_mask:0xf bank_mask:0xf bound_ctrl:1
	v_mov_b32_dpp v79, v73 row_shr:1 row_mask:0xf bank_mask:0xf bound_ctrl:1
	v_pk_mul_f32 v[214:215], v[214:215], v[220:221]
	v_pk_fma_f32 v[220:221], v[184:185], v[206:207], v[210:211]
	v_pk_fma_f32 v[76:77], v[196:197], v[76:77], v[218:219]
	v_mov_b32_dpp v224, v172 row_shr:1 row_mask:0xf bank_mask:0xf bound_ctrl:1
	v_mov_b32_dpp v225, v173 row_shr:1 row_mask:0xf bank_mask:0xf bound_ctrl:1
	v_pk_fma_f32 v[220:221], v[202:203], v[78:79], v[220:221]
	v_pk_mul_f32 v[76:77], v[102:103], v[76:77]
	v_pk_fma_f32 v[102:103], v[66:67], v[204:205], v[208:209]
	v_pk_fma_f32 v[218:219], v[198:199], v[224:225], v[220:221]
	v_pk_fma_f32 v[102:103], v[174:175], v[200:201], v[102:103]
	v_pk_mul_f32 v[218:219], v[110:111], v[218:219]
	v_pk_fma_f32 v[110:111], v[70:71], v[206:207], v[210:211]
	v_pk_fma_f32 v[64:65], v[196:197], v[64:65], v[102:103]
	v_pk_fma_f32 v[102:103], v[172:173], v[206:207], v[210:211]
	v_pk_fma_f32 v[110:111], v[184:185], v[202:203], v[110:111]
	v_pk_fma_f32 v[102:103], v[70:71], v[202:203], v[102:103]
	v_pk_fma_f32 v[78:79], v[198:199], v[78:79], v[110:111]
	v_pk_mul_f32 v[64:65], v[98:99], v[64:65]
	v_pk_fma_f32 v[98:99], v[74:75], v[204:205], v[208:209]
	v_pk_fma_f32 v[102:103], v[184:185], v[198:199], v[102:103]
	v_pk_mul_f32 v[78:79], v[106:107], v[78:79]
	v_pk_fma_f32 v[98:99], v[66:67], v[200:201], v[98:99]
	v_pk_mul_f32 v[220:221], v[222:223], v[102:103]
	v_pk_fma_f32 v[102:103], v[68:69], v[204:205], v[208:209]
	v_pk_fma_f32 v[106:107], v[72:73], v[206:207], v[210:211]
	v_pk_fma_f32 v[98:99], v[174:175], v[196:197], v[98:99]
	v_pk_fma_f32 v[106:107], v[172:173], v[202:203], v[106:107]
	v_pk_fma_f32 v[102:103], v[74:75], v[200:201], v[102:103]
	v_pk_mul_f32 v[98:99], v[212:213], v[98:99]
	v_pk_fma_f32 v[102:103], v[66:67], v[196:197], v[102:103]
	v_pk_fma_f32 v[106:107], v[70:71], v[198:199], v[106:107]
	v_pk_mul_f32 v[198:199], v[216:217], v[102:103]
	v_pk_mul_f32 v[196:197], v[214:215], v[106:107]
	v_cvt_pk_bf16_f32 v110, v76, v77
	v_cvt_pk_bf16_f32 v111, v218, v219
	v_cvt_pk_bf16_f32 v106, v64, v65
	v_cvt_pk_bf16_f32 v107, v78, v79
	v_cvt_pk_bf16_f32 v102, v98, v99
	v_cvt_pk_bf16_f32 v103, v220, v221
	v_cvt_pk_bf16_f32 v98, v198, v199
	s_nop 0
	v_cvt_pk_bf16_f32 v99, v196, v197
	v_lshlrev_b64 v[64:65], 1, v[158:159]
	s_and_saveexec_b64 s[8:9], s[0:1]
	s_cbranch_execz .LBB0_750
	v_mov_b64_e32 v[76:77], s[22:23]
	v_mad_i64_i32 v[78:79], s[10:11], v148, s56, v[76:77]
	v_mad_i64_i32 v[76:77], s[10:11], v150, s56, v[76:77]
	v_lshl_add_u64 v[78:79], v[78:79], 0, v[64:65]
	v_lshl_add_u64 v[76:77], v[76:77], 0, v[64:65]
	global_store_dwordx4 v[78:79], v[108:111], off
	global_store_dwordx4 v[76:77], v[104:107], off

; #define PG8_LAS __attribute__((address_space(3)))
; __device__ __forceinline__ float row_up1(float v) { return dpp_mov<0x111>(v); }
; __device__ __forceinline__ float siluf_(float x) { return x * __builtin_amdgcn_rcpf(1.0f + __builtin_amdgcn_exp2f(x * -1.4426950408889634f)); }
;     __device__ __forceinline__ void operator()(f32x4 (&acc)[2][2][4][2], const pg8::Unit& u, int wr, int wc, int fr, int fq) const {
;     ...
;         for (int ai = 0; ai < 2; ++ai) {
;             const int tb = u.pm * 256 + ai * 128 + wr * 64 + 4 * fr;
;             float rstd[4];
; #pragma unroll
;             for (int m = 0; m < 4; ++m) { const f32x4 sv = *(const f32x4*)(SS + (size_t)(tb + m) * 16 + 4 * fq); float s = (sv[0] + sv[1]) + (sv[2] + sv[3]); s += __shfl_xor(s, 16); s += __shfl_xor(s, 32);
;                 rstd[m] = rsqrtf(s * (1.0f / 1024.0f) + EPS); }
;             u32x2 pk[2][4];
; #pragma unroll
;             for (int n = 0; n < 2; ++n) {
;                 f32x4 g[4];
;                 {   const PG8_LAS unsigned char* wq = wl + (8 * fq + 4 * n) * 4;
;                     const f32x4 w0 = *(const PG8_LAS f32x4*)(wq), w1 = *(const PG8_LAS f32x4*)(wq + 256), w2 = *(const PG8_LAS f32x4*)(wq + 512), bb = *(const PG8_LAS f32x4*)(wq + 768);
;                     const f32x4 x0 = acc[ai][0][0][n] * rstd[0], x1 = acc[ai][0][1][n] * rstd[1], x2 = acc[ai][0][2][n] * rstd[2], x3 = acc[ai][0][3][n] * rstd[3];
;                     acc[ai][0][0][n] = x0; acc[ai][0][1][n] = x1; acc[ai][0][2][n] = x2; acc[ai][0][3][n] = x3;
;                     f32x4 p1, p2;
; #pragma unroll
;                     for (int c = 0; c < 4; ++c) { p1[c] = row_up1(x3[c]); p2[c] = row_up1(x2[c]); }
;                     g[0] = bb + w2 * x0 + w1 * p1 + w0 * p2; g[1] = bb + w2 * x1 + w1 * x0 + w0 * p1;
;                     g[2] = bb + w2 * x2 + w1 * x1 + w0 * x0; g[3] = bb + w2 * x3 + w1 * x2 + w0 * x1;
; #pragma unroll
;                     for (int m = 0; m < 4; ++m)
; #pragma unroll
;                         for (int c = 0; c < 4; ++c) g[m][c] = siluf_(g[m][c]);
.LBB0_754:
	s_or_b64 exec, exec, s[8:9]
	s_nop 0
	v_add_u32_e32 v66, 0x80, v148
	v_ashrrev_i32_e32 v67, 31, v66
	v_lshlrev_b64 v[68:69], 6, v[66:67]
	v_lshl_add_u64 v[70:71], v[138:139], 0, v[68:69]
	v_add_u32_e32 v68, 0x81, v148
	v_ashrrev_i32_e32 v69, 31, v68
	v_lshlrev_b64 v[72:73], 6, v[68:69]
	v_lshl_add_u64 v[72:73], v[138:139], 0, v[72:73]
	global_load_dwordx4 v[74:77], v[70:71], off
	global_load_dwordx4 v[78:81], v[72:73], off
	v_add_u32_e32 v70, 0x82, v148
	v_ashrrev_i32_e32 v71, 31, v70
	v_lshlrev_b64 v[72:73], 6, v[70:71]
	v_lshl_add_u64 v[72:73], v[138:139], 0, v[72:73]
	global_load_dwordx4 v[82:85], v[72:73], off
	v_add_u32_e32 v72, 0x83, v148
	v_ashrrev_i32_e32 v73, 31, v72
	v_lshlrev_b64 v[86:87], 6, v[72:73]
	v_lshl_add_u64 v[86:87], v[138:139], 0, v[86:87]
	global_load_dwordx4 v[86:89], v[86:87], off
	s_waitcnt vmcnt(3)
	v_mov_b32_e32 v90, v75
	v_mov_b32_e32 v91, v76
	v_mov_b32_e32 v75, v77
	s_waitcnt vmcnt(2)
	v_mov_b32_e32 v76, v79
	v_mov_b32_e32 v77, v80
	v_mov_b32_e32 v79, v81
	s_waitcnt vmcnt(1)
	v_mov_b32_e32 v80, v83
	v_mov_b32_e32 v81, v84
	v_mov_b32_e32 v83, v85
	v_pk_add_f32 v[74:75], v[90:91], v[74:75]
	v_pk_add_f32 v[76:77], v[76:77], v[78:79]
	s_waitcnt vmcnt(0)
	v_mov_b32_e32 v84, v87
	v_mov_b32_e32 v85, v88
	v_mov_b32_e32 v87, v89
	v_pk_add_f32 v[78:79], v[80:81], v[82:83]
	v_pk_add_f32 v[80:81], v[84:85], v[86:87]
	v_mov_b32_e32 v82, v76
	v_mov_b32_e32 v83, v74
	v_mov_b32_e32 v74, v77
	v_mov_b32_e32 v76, v80
	v_mov_b32_e32 v77, v78
	v_mov_b32_e32 v78, v81
	v_pk_add_f32 v[74:75], v[82:83], v[74:75]
	v_pk_add_f32 v[76:77], v[76:77], v[78:79]
	ds_bpermute_b32 v79, v149, v75
	ds_bpermute_b32 v78, v149, v74
	ds_bpermute_b32 v81, v149, v77
	ds_bpermute_b32 v80, v149, v76
	v_mov_b64_e32 v[82:83], s[38:39]
	s_waitcnt lgkmcnt(2)
	v_pk_add_f32 v[84:85], v[74:75], v[78:79]
	ds_bpermute_b32 v89, v151, v85
	s_waitcnt lgkmcnt(1)
	v_pk_add_f32 v[86:87], v[76:77], v[80:81]
	ds_bpermute_b32 v88, v151, v84
	ds_bpermute_b32 v99, v151, v87
	ds_bpermute_b32 v98, v151, v86
	ds_read_b128 v[74:77], v195
	ds_read_b128 v[78:81], v195 offset:256
	ds_read_b128 v[90:93], v195 offset:512
	ds_read_b128 v[94:97], v195 offset:768
	s_waitcnt lgkmcnt(6)
	v_pk_add_f32 v[84:85], v[84:85], v[88:89]
	s_nop 0
	v_pk_fma_f32 v[84:85], v[84:85], s[24:25], v[82:83] op_sel_hi:[1,0,0]
	s_waitcnt lgkmcnt(4)
	v_pk_add_f32 v[86:87], v[86:87], v[98:99]
	v_pk_fma_f32 v[82:83], v[86:87], s[24:25], v[82:83] op_sel_hi:[1,0,0]
	v_rsq_f32_e32 v67, v85
	v_rsq_f32_e32 v73, v82
	v_rsq_f32_e32 v69, v84
	v_rsq_f32_e32 v71, v83
	v_mov_b32_e32 v88, v67
	v_mov_b32_e32 v82, v73
	v_mov_b32_e32 v84, v71
	v_pk_mul_f32 v[60:61], v[60:61], v[88:89] op_sel_hi:[1,0]
	v_pk_mul_f32 v[48:49], v[48:49], v[82:83] op_sel_hi:[1,0]
	v_pk_mul_f32 v[52:53], v[52:53], v[84:85] op_sel_hi:[1,0]
	s_waitcnt lgkmcnt(0)
	v_pk_fma_f32 v[108:109], v[90:91], v[60:61], v[94:95]
	v_mov_b32_dpp v98, v48 row_shr:1 row_mask:0xf bank_mask:0xf bound_ctrl:1
	v_mov_b32_dpp v99, v49 row_shr:1 row_mask:0xf bank_mask:0xf bound_ctrl:1
	v_mov_b32_dpp v100, v52 row_shr:1 row_mask:0xf bank_mask:0xf bound_ctrl:1
	v_mov_b32_dpp v101, v53 row_shr:1 row_mask:0xf bank_mask:0xf bound_ctrl:1
	v_pk_fma_f32 v[108:109], v[78:79], v[98:99], v[108:109]
	v_mov_b32_e32 v86, v69
	v_pk_fma_f32 v[100:101], v[74:75], v[100:101], v[108:109]
	v_pk_mul_f32 v[62:63], v[62:63], v[88:89] op_sel_hi:[1,0]
	v_exp_f32_e32 v242, v100
	v_pk_mul_f32 v[50:51], v[50:51], v[82:83] op_sel_hi:[1,0]
	v_exp_f32_e32 v243, v101
	v_pk_mul_f32 v[56:57], v[56:57], v[86:87] op_sel_hi:[1,0]
	v_pk_mul_f32 v[54:55], v[54:55], v[84:85] op_sel_hi:[1,0]
	v_mov_b32_dpp v102, v50 row_shr:1 row_mask:0xf bank_mask:0xf bound_ctrl:1
	v_mov_b32_dpp v103, v51 row_shr:1 row_mask:0xf bank_mask:0xf bound_ctrl:1
	v_pk_fma_f32 v[106:107], v[92:93], v[62:63], v[96:97]
	v_mov_b32_dpp v104, v54 row_shr:1 row_mask:0xf bank_mask:0xf bound_ctrl:1
	v_mov_b32_dpp v105, v55 row_shr:1 row_mask:0xf bank_mask:0xf bound_ctrl:1
	v_pk_fma_f32 v[112:113], v[90:91], v[56:57], v[94:95]
	v_pk_fma_f32 v[106:107], v[80:81], v[102:103], v[106:107]
	v_pk_fma_f32 v[108:109], v[90:91], v[52:53], v[94:95]
	v_pk_fma_f32 v[90:91], v[90:91], v[48:49], v[94:95]
	v_pk_fma_f32 v[112:113], v[78:79], v[60:61], v[112:113]
	v_pk_fma_f32 v[104:105], v[76:77], v[104:105], v[106:107]
	v_pk_fma_f32 v[108:109], v[78:79], v[56:57], v[108:109]
	v_pk_fma_f32 v[78:79], v[78:79], v[52:53], v[90:91]
	v_pk_fma_f32 v[98:99], v[74:75], v[98:99], v[112:113]
	v_pk_fma_f32 v[108:109], v[74:75], v[60:61], v[108:109]
	v_pk_fma_f32 v[116:117], v[74:75], v[56:57], v[78:79]
	v_pk_add_f32 v[242:243], v[242:243], v[250:251]
	v_rcp_f32_e32 v74, v242
	v_exp_f32_e32 v244, v104
	v_exp_f32_e32 v245, v105
	v_pk_mul_f32 v[58:59], v[58:59], v[86:87] op_sel_hi:[1,0]
	v_pk_fma_f32 v[106:107], v[92:93], v[54:55], v[96:97]
	v_pk_fma_f32 v[110:111], v[92:93], v[58:59], v[96:97]
	v_pk_fma_f32 v[92:93], v[92:93], v[50:51], v[96:97]
	v_pk_fma_f32 v[110:111], v[80:81], v[62:63], v[110:111]
	v_pk_fma_f32 v[106:107], v[80:81], v[58:59], v[106:107]
	v_pk_fma_f32 v[80:81], v[80:81], v[54:55], v[92:93]
	v_rcp_f32_e32 v75, v243
	v_pk_fma_f32 v[102:103], v[76:77], v[102:103], v[110:111]
	v_pk_fma_f32 v[106:107], v[76:77], v[62:63], v[106:107]
	v_pk_fma_f32 v[114:115], v[76:77], v[58:59], v[80:81]
	v_pk_add_f32 v[244:245], v[244:245], v[250:251]
	v_rcp_f32_e32 v76, v244
	v_rcp_f32_e32 v77, v245
	v_exp_f32_e32 v246, v98
	v_exp_f32_e32 v247, v99
	v_pk_mul_f32 v[118:119], v[100:101], v[74:75]
	v_pk_add_f32 v[246:247], v[246:247], v[250:251]
	v_rcp_f32_e32 v74, v246
	v_exp_f32_e32 v248, v102
	v_exp_f32_e32 v249, v103
	v_rcp_f32_e32 v75, v247
; #define PG8_LAS __attribute__((address_space(3)))
; __device__ __forceinline__ unsigned pk2(float a, float b) { return pg8::cvt_pk_bf16(a, b); }
; __device__ __forceinline__ float row_up1(float v) { return dpp_mov<0x111>(v); }
; __device__ __forceinline__ float siluf_(float x) { return x * __builtin_amdgcn_rcpf(1.0f + __builtin_amdgcn_exp2f(x * -1.4426950408889634f)); }
;     __device__ __forceinline__ void operator()(f32x4 (&acc)[2][2][4][2], const pg8::Unit& u, int wr, int wc, int fr, int fq) const {
;     ...
;                     g[0] = bb + w2 * x0 + w1 * p1 + w0 * p2; g[1] = bb + w2 * x1 + w1 * x0 + w0 * p1;
;                     g[2] = bb + w2 * x2 + w1 * x1 + w0 * x0; g[3] = bb + w2 * x3 + w1 * x2 + w0 * x1;
; #pragma unroll
;                     for (int m = 0; m < 4; ++m)
; #pragma unroll
;                         for (int c = 0; c < 4; ++c) g[m][c] = siluf_(g[m][c]);
;                 }
;                 __builtin_amdgcn_sched_barrier(0);
;                 {   const PG8_LAS unsigned char* wq = wl + 128 + (8 * fq + 4 * n) * 4;
;                     const f32x4 w0 = *(const PG8_LAS f32x4*)(wq), w1 = *(const PG8_LAS f32x4*)(wq + 256), w2 = *(const PG8_LAS f32x4*)(wq + 512), bb = *(const PG8_LAS f32x4*)(wq + 768);
;                     const f32x4 x0 = acc[ai][1][0][n] * rstd[0], x1 = acc[ai][1][1][n] * rstd[1], x2 = acc[ai][1][2][n] * rstd[2], x3 = acc[ai][1][3][n] * rstd[3];
;                     acc[ai][1][0][n] = x0; acc[ai][1][1][n] = x1; acc[ai][1][2][n] = x2; acc[ai][1][3][n] = x3;
;                     f32x4 p1, p2;
; #pragma unroll
;                     for (int c = 0; c < 4; ++c) { p1[c] = row_up1(x3[c]); p2[c] = row_up1(x2[c]); }
;                     g[0] *= bb + w2 * x0 + w1 * p1 + w0 * p2; g[1] *= bb + w2 * x1 + w1 * x0 + w0 * p1;
;                     g[2] *= bb + w2 * x2 + w1 * x1 + w0 * x0; g[3] *= bb + w2 * x3 + w1 * x2 + w0 * x1;
;                 }
; #pragma unroll
;                 for (int m = 0; m < 4; ++m) { pk[n][m].x = pk2(g[m][0], g[m][1]); pk[n][m].y = pk2(g[m][2], g[m][3]); }
	v_pk_mul_f32 v[120:121], v[104:105], v[76:77]
	v_pk_add_f32 v[248:249], v[248:249], v[250:251]
	v_rcp_f32_e32 v76, v248
	v_rcp_f32_e32 v77, v249
	v_exp_f32_e32 v240, v108
	v_exp_f32_e32 v241, v109
	v_pk_mul_f32 v[122:123], v[98:99], v[74:75]
	v_pk_add_f32 v[240:241], v[240:241], v[250:251]
	v_rcp_f32_e32 v74, v240
	v_exp_f32_e32 v242, v106
	v_exp_f32_e32 v243, v107
	v_rcp_f32_e32 v75, v241
	v_pk_add_f32 v[242:243], v[242:243], v[250:251]
	v_rcp_f32_e32 v78, v242
	v_exp_f32_e32 v244, v116
	v_exp_f32_e32 v245, v117
	v_rcp_f32_e32 v79, v243
	v_pk_add_f32 v[244:245], v[244:245], v[250:251]
	v_rcp_f32_e32 v124, v244
	v_exp_f32_e32 v246, v114
	v_exp_f32_e32 v247, v115
	v_rcp_f32_e32 v125, v245
	v_pk_add_f32 v[246:247], v[246:247], v[250:251]
	v_rcp_f32_e32 v126, v246
	v_rcp_f32_e32 v127, v247
	v_pk_mul_f32 v[148:149], v[102:103], v[76:77]
	v_pk_mul_f32 v[150:151], v[108:109], v[74:75]
	v_pk_mul_f32 v[154:155], v[106:107], v[78:79]
	ds_read_b128 v[98:101], v195 offset:128
	ds_read_b128 v[102:105], v195 offset:384
	ds_read_b128 v[106:109], v195 offset:640
	ds_read_b128 v[110:113], v195 offset:896
	v_pk_mul_f32 v[90:91], v[44:45], v[88:89] op_sel_hi:[1,0]
	v_pk_mul_f32 v[78:79], v[32:33], v[82:83] op_sel_hi:[1,0]
	v_pk_mul_f32 v[94:95], v[36:37], v[84:85] op_sel_hi:[1,0]
	v_pk_mul_f32 v[74:75], v[40:41], v[86:87] op_sel_hi:[1,0]
	v_mov_b32_dpp v32, v78 row_shr:1 row_mask:0xf bank_mask:0xf bound_ctrl:1
	v_mov_b32_dpp v33, v79 row_shr:1 row_mask:0xf bank_mask:0xf bound_ctrl:1
	s_waitcnt lgkmcnt(0)
	v_pk_fma_f32 v[44:45], v[90:91], v[106:107], v[110:111]
	v_pk_mul_f32 v[80:81], v[34:35], v[82:83] op_sel_hi:[1,0]
	v_mov_b32_dpp v34, v94 row_shr:1 row_mask:0xf bank_mask:0xf bound_ctrl:1
	v_mov_b32_dpp v35, v95 row_shr:1 row_mask:0xf bank_mask:0xf bound_ctrl:1
	v_pk_fma_f32 v[44:45], v[102:103], v[32:33], v[44:45]
	v_pk_mul_f32 v[92:93], v[46:47], v[88:89] op_sel_hi:[1,0]
	v_pk_fma_f32 v[34:35], v[98:99], v[34:35], v[44:45]
	v_pk_fma_f32 v[44:45], v[74:75], v[106:107], v[110:111]
	v_pk_mul_f32 v[96:97], v[38:39], v[84:85] op_sel_hi:[1,0]
	v_mov_b32_dpp v36, v80 row_shr:1 row_mask:0xf bank_mask:0xf bound_ctrl:1
	v_mov_b32_dpp v37, v81 row_shr:1 row_mask:0xf bank_mask:0xf bound_ctrl:1
	v_pk_fma_f32 v[46:47], v[92:93], v[108:109], v[112:113]
	v_pk_fma_f32 v[44:45], v[90:91], v[102:103], v[44:45]
	v_pk_mul_f32 v[76:77], v[42:43], v[86:87] op_sel_hi:[1,0]
	v_mov_b32_dpp v38, v96 row_shr:1 row_mask:0xf bank_mask:0xf bound_ctrl:1
	v_mov_b32_dpp v39, v97 row_shr:1 row_mask:0xf bank_mask:0xf bound_ctrl:1
	v_pk_fma_f32 v[46:47], v[104:105], v[36:37], v[46:47]
	v_pk_fma_f32 v[32:33], v[98:99], v[32:33], v[44:45]
	v_pk_fma_f32 v[44:45], v[94:95], v[106:107], v[110:111]
	v_pk_fma_f32 v[38:39], v[100:101], v[38:39], v[46:47]
	v_pk_fma_f32 v[46:47], v[76:77], v[108:109], v[112:113]
	v_pk_fma_f32 v[44:45], v[74:75], v[102:103], v[44:45]
	v_pk_fma_f32 v[46:47], v[92:93], v[104:105], v[46:47]
	v_pk_fma_f32 v[44:45], v[90:91], v[98:99], v[44:45]
	v_pk_mul_f32 v[42:43], v[114:115], v[126:127]
	v_pk_fma_f32 v[36:37], v[100:101], v[36:37], v[46:47]
	v_pk_fma_f32 v[46:47], v[96:97], v[108:109], v[112:113]
	v_pk_mul_f32 v[114:115], v[44:45], v[150:151]
	v_pk_fma_f32 v[44:45], v[78:79], v[106:107], v[110:111]
	v_pk_fma_f32 v[106:107], v[80:81], v[108:109], v[112:113]
	v_pk_fma_f32 v[46:47], v[76:77], v[104:105], v[46:47]
	v_pk_fma_f32 v[104:105], v[96:97], v[104:105], v[106:107]
	v_pk_fma_f32 v[44:45], v[94:95], v[102:103], v[44:45]
	v_pk_mul_f32 v[40:41], v[116:117], v[124:125]
	v_pk_fma_f32 v[46:47], v[92:93], v[100:101], v[46:47]
	v_pk_fma_f32 v[44:45], v[74:75], v[98:99], v[44:45]
	v_pk_fma_f32 v[98:99], v[76:77], v[100:101], v[104:105]
	v_pk_mul_f32 v[38:39], v[120:121], v[38:39]
	v_pk_mul_f32 v[34:35], v[118:119], v[34:35]
	v_pk_mul_f32 v[36:37], v[148:149], v[36:37]
	v_pk_mul_f32 v[32:33], v[122:123], v[32:33]
	v_pk_mul_f32 v[46:47], v[46:47], v[154:155]
	v_pk_mul_f32 v[42:43], v[98:99], v[42:43]
	v_pk_mul_f32 v[98:99], v[44:45], v[40:41]
	v_cvt_pk_bf16_f32 v44, v34, v35
	v_cvt_pk_bf16_f32 v45, v38, v39
	v_cvt_pk_bf16_f32 v40, v32, v33
	v_cvt_pk_bf16_f32 v41, v36, v37
	v_cvt_pk_bf16_f32 v36, v114, v115
	v_cvt_pk_bf16_f32 v37, v46, v47
	s_nop 0
	v_cvt_pk_bf16_f32 v32, v98, v99
	v_cvt_pk_bf16_f32 v33, v42, v43
	ds_read_b128 v[102:105], v195 offset:16
	ds_read_b128 v[106:109], v195 offset:272
	ds_read_b128 v[110:113], v195 offset:528
	ds_read_b128 v[114:117], v195 offset:784
	v_pk_mul_f32 v[98:99], v[16:17], v[88:89] op_sel_hi:[1,0]
	v_pk_mul_f32 v[16:17], v[20:21], v[86:87] op_sel_hi:[1,0]
	v_pk_mul_f32 v[20:21], v[28:29], v[82:83] op_sel_hi:[1,0]
	v_pk_mul_f32 v[24:25], v[24:25], v[84:85] op_sel_hi:[1,0]
	s_waitcnt lgkmcnt(0)
; #define PG8_LAS __attribute__((address_space(3)))
; __device__ __forceinline__ unsigned pk2(float a, float b) { return pg8::cvt_pk_bf16(a, b); }
; __device__ __forceinline__ float row_up1(float v) { return dpp_mov<0x111>(v); }
; __device__ __forceinline__ float siluf_(float x) { return x * __builtin_amdgcn_rcpf(1.0f + __builtin_amdgcn_exp2f(x * -1.4426950408889634f)); }
;     __device__ __forceinline__ void operator()(f32x4 (&acc)[2][2][4][2], const pg8::Unit& u, int wr, int wc, int fr, int fq) const {
;     ...
;                     g[0] = bb + w2 * x0 + w1 * p1 + w0 * p2; g[1] = bb + w2 * x1 + w1 * x0 + w0 * p1;
;                     g[2] = bb + w2 * x2 + w1 * x1 + w0 * x0; g[3] = bb + w2 * x3 + w1 * x2 + w0 * x1;
; #pragma unroll
;                     for (int m = 0; m < 4; ++m)
; #pragma unroll
;                         for (int c = 0; c < 4; ++c) g[m][c] = siluf_(g[m][c]);
;                 }
;                 __builtin_amdgcn_sched_barrier(0);
;                 {   const PG8_LAS unsigned char* wq = wl + 128 + (8 * fq + 4 * n) * 4;
;                     const f32x4 w0 = *(const PG8_LAS f32x4*)(wq), w1 = *(const PG8_LAS f32x4*)(wq + 256), w2 = *(const PG8_LAS f32x4*)(wq + 512), bb = *(const PG8_LAS f32x4*)(wq + 768);
;                     const f32x4 x0 = acc[ai][1][0][n] * rstd[0], x1 = acc[ai][1][1][n] * rstd[1], x2 = acc[ai][1][2][n] * rstd[2], x3 = acc[ai][1][3][n] * rstd[3];
;                     acc[ai][1][0][n] = x0; acc[ai][1][1][n] = x1; acc[ai][1][2][n] = x2; acc[ai][1][3][n] = x3;
;                     f32x4 p1, p2;
; #pragma unroll
;                     for (int c = 0; c < 4; ++c) { p1[c] = row_up1(x3[c]); p2[c] = row_up1(x2[c]); }
;                     g[0] *= bb + w2 * x0 + w1 * p1 + w0 * p2; g[1] *= bb + w2 * x1 + w1 * x0 + w0 * p1;
;                     g[2] *= bb + w2 * x2 + w1 * x1 + w0 * x0; g[3] *= bb + w2 * x3 + w1 * x2 + w0 * x1;
;                 }
; #pragma unroll
;                 for (int m = 0; m < 4; ++m) { pk[n][m].x = pk2(g[m][0], g[m][1]); pk[n][m].y = pk2(g[m][2], g[m][3]); }
;                 __builtin_amdgcn_sched_barrier(0);
;             }
; #pragma unroll
;             for (int m = 0; m < 4; ++m) if (fr != 0 || m >= 2) {
	v_pk_fma_f32 v[46:47], v[98:99], v[110:111], v[114:115]
	v_mov_b32_dpp v28, v20 row_shr:1 row_mask:0xf bank_mask:0xf bound_ctrl:1
	v_mov_b32_dpp v29, v21 row_shr:1 row_mask:0xf bank_mask:0xf bound_ctrl:1
	v_pk_mul_f32 v[100:101], v[18:19], v[88:89] op_sel_hi:[1,0]
	v_pk_mul_f32 v[18:19], v[22:23], v[86:87] op_sel_hi:[1,0]
	v_pk_mul_f32 v[22:23], v[30:31], v[82:83] op_sel_hi:[1,0]
	v_mov_b32_dpp v30, v24 row_shr:1 row_mask:0xf bank_mask:0xf bound_ctrl:1
	v_mov_b32_dpp v31, v25 row_shr:1 row_mask:0xf bank_mask:0xf bound_ctrl:1
	v_pk_fma_f32 v[46:47], v[106:107], v[28:29], v[46:47]
	v_pk_mul_f32 v[26:27], v[26:27], v[84:85] op_sel_hi:[1,0]
	v_pk_fma_f32 v[30:31], v[102:103], v[30:31], v[46:47]
	v_pk_fma_f32 v[46:47], v[16:17], v[110:111], v[114:115]
	v_exp_f32_e32 v248, v30
	v_exp_f32_e32 v249, v31
	v_mov_b32_dpp v34, v22 row_shr:1 row_mask:0xf bank_mask:0xf bound_ctrl:1
	v_mov_b32_dpp v35, v23 row_shr:1 row_mask:0xf bank_mask:0xf bound_ctrl:1
	v_pk_fma_f32 v[42:43], v[100:101], v[112:113], v[116:117]
	v_pk_fma_f32 v[46:47], v[98:99], v[106:107], v[46:47]
	v_mov_b32_dpp v38, v26 row_shr:1 row_mask:0xf bank_mask:0xf bound_ctrl:1
	v_mov_b32_dpp v39, v27 row_shr:1 row_mask:0xf bank_mask:0xf bound_ctrl:1
	v_pk_fma_f32 v[42:43], v[108:109], v[34:35], v[42:43]
	v_pk_fma_f32 v[28:29], v[102:103], v[28:29], v[46:47]
	v_pk_fma_f32 v[46:47], v[24:25], v[110:111], v[114:115]
	v_pk_fma_f32 v[110:111], v[20:21], v[110:111], v[114:115]
	v_pk_fma_f32 v[38:39], v[104:105], v[38:39], v[42:43]
	v_pk_fma_f32 v[46:47], v[16:17], v[106:107], v[46:47]
	v_pk_fma_f32 v[106:107], v[24:25], v[106:107], v[110:111]
	v_pk_fma_f32 v[46:47], v[98:99], v[102:103], v[46:47]
	v_pk_fma_f32 v[120:121], v[16:17], v[102:103], v[106:107]
	v_pk_add_f32 v[248:249], v[248:249], v[250:251]
	v_rcp_f32_e32 v102, v248
	v_exp_f32_e32 v240, v38
	v_pk_fma_f32 v[42:43], v[18:19], v[112:113], v[116:117]
	v_exp_f32_e32 v241, v39
	v_pk_fma_f32 v[42:43], v[100:101], v[108:109], v[42:43]
	v_rcp_f32_e32 v103, v249
	v_pk_fma_f32 v[34:35], v[104:105], v[34:35], v[42:43]
	v_pk_fma_f32 v[42:43], v[26:27], v[112:113], v[116:117]
	v_pk_fma_f32 v[112:113], v[22:23], v[112:113], v[116:117]
	v_pk_fma_f32 v[42:43], v[18:19], v[108:109], v[42:43]
	v_pk_fma_f32 v[108:109], v[26:27], v[108:109], v[112:113]
	v_pk_fma_f32 v[42:43], v[100:101], v[104:105], v[42:43]
	v_pk_fma_f32 v[118:119], v[18:19], v[104:105], v[108:109]
	v_pk_add_f32 v[240:241], v[240:241], v[250:251]
	v_rcp_f32_e32 v104, v240
	v_rcp_f32_e32 v105, v241
	v_exp_f32_e32 v242, v34
	v_pk_mul_f32 v[122:123], v[30:31], v[102:103]
	v_exp_f32_e32 v243, v35
	v_exp_f32_e32 v244, v28
	v_exp_f32_e32 v245, v29
	v_pk_add_f32 v[242:243], v[242:243], v[250:251]
	v_rcp_f32_e32 v102, v242
	v_pk_add_f32 v[244:245], v[244:245], v[250:251]
	v_rcp_f32_e32 v103, v243
	v_rcp_f32_e32 v30, v244
	v_rcp_f32_e32 v31, v245
	v_exp_f32_e32 v246, v46
	v_exp_f32_e32 v247, v47
	v_pk_mul_f32 v[124:125], v[28:29], v[30:31]
	v_pk_add_f32 v[246:247], v[246:247], v[250:251]
	v_exp_f32_e32 v248, v120
	v_exp_f32_e32 v249, v121
	v_exp_f32_e32 v240, v42
	v_exp_f32_e32 v241, v43
	v_pk_add_f32 v[248:249], v[248:249], v[250:251]
	v_rcp_f32_e32 v126, v248
	v_pk_add_f32 v[240:241], v[240:241], v[250:251]
	v_exp_f32_e32 v242, v118
	v_rcp_f32_e32 v28, v246
	v_rcp_f32_e32 v29, v247
	v_rcp_f32_e32 v30, v240
	v_rcp_f32_e32 v31, v241
	v_exp_f32_e32 v243, v119
	v_rcp_f32_e32 v127, v249
	v_pk_mul_f32 v[38:39], v[38:39], v[104:105]
	v_pk_add_f32 v[242:243], v[242:243], v[250:251]
	v_rcp_f32_e32 v148, v242
	v_pk_mul_f32 v[34:35], v[34:35], v[102:103]
	v_pk_mul_f32 v[46:47], v[46:47], v[28:29]
	v_pk_mul_f32 v[42:43], v[42:43], v[30:31]
	v_rcp_f32_e32 v149, v243
	ds_read_b128 v[102:105], v195 offset:144
	ds_read_b128 v[106:109], v195 offset:400
	ds_read_b128 v[110:113], v195 offset:656
	ds_read_b128 v[114:117], v195 offset:912
	v_pk_mul_f32 v[30:31], v[2:3], v[88:89] op_sel_hi:[1,0]
	v_pk_mul_f32 v[28:29], v[0:1], v[88:89] op_sel_hi:[1,0]
	v_pk_mul_f32 v[2:3], v[6:7], v[86:87] op_sel_hi:[1,0]
	v_pk_mul_f32 v[0:1], v[4:5], v[86:87] op_sel_hi:[1,0]
	v_pk_mul_f32 v[6:7], v[14:15], v[82:83] op_sel_hi:[1,0]
	v_pk_mul_f32 v[4:5], v[12:13], v[82:83] op_sel_hi:[1,0]
	v_pk_mul_f32 v[10:11], v[10:11], v[84:85] op_sel_hi:[1,0]
	v_pk_mul_f32 v[8:9], v[8:9], v[84:85] op_sel_hi:[1,0]
	v_mov_b32_dpp v12, v4 row_shr:1 row_mask:0xf bank_mask:0xf bound_ctrl:1
	v_mov_b32_dpp v13, v5 row_shr:1 row_mask:0xf bank_mask:0xf bound_ctrl:1
	v_mov_b32_dpp v82, v6 row_shr:1 row_mask:0xf bank_mask:0xf bound_ctrl:1
	v_mov_b32_dpp v83, v7 row_shr:1 row_mask:0xf bank_mask:0xf bound_ctrl:1
	v_pk_mul_f32 v[86:87], v[120:121], v[126:127]
	v_pk_mul_f32 v[88:89], v[118:119], v[148:149]
	s_waitcnt lgkmcnt(0)
	v_pk_fma_f32 v[118:119], v[28:29], v[110:111], v[114:115]
	v_pk_fma_f32 v[120:121], v[30:31], v[112:113], v[116:117]
	v_mov_b32_dpp v14, v8 row_shr:1 row_mask:0xf bank_mask:0xf bound_ctrl:1
	v_mov_b32_dpp v15, v9 row_shr:1 row_mask:0xf bank_mask:0xf bound_ctrl:1
	v_mov_b32_dpp v84, v10 row_shr:1 row_mask:0xf bank_mask:0xf bound_ctrl:1
	v_mov_b32_dpp v85, v11 row_shr:1 row_mask:0xf bank_mask:0xf bound_ctrl:1
	v_pk_fma_f32 v[120:121], v[108:109], v[82:83], v[120:121]
	v_pk_fma_f32 v[118:119], v[106:107], v[12:13], v[118:119]
	v_pk_fma_f32 v[84:85], v[104:105], v[84:85], v[120:121]
	v_pk_fma_f32 v[14:15], v[102:103], v[14:15], v[118:119]
	v_pk_fma_f32 v[118:119], v[2:3], v[112:113], v[116:117]
	v_pk_mul_f32 v[38:39], v[38:39], v[84:85]
	v_pk_fma_f32 v[84:85], v[0:1], v[110:111], v[114:115]
	v_pk_fma_f32 v[118:119], v[30:31], v[108:109], v[118:119]
	v_pk_fma_f32 v[84:85], v[28:29], v[106:107], v[84:85]
	v_pk_fma_f32 v[82:83], v[104:105], v[82:83], v[118:119]
	v_pk_fma_f32 v[12:13], v[102:103], v[12:13], v[84:85]
	v_pk_mul_f32 v[34:35], v[34:35], v[82:83]
	v_pk_fma_f32 v[82:83], v[8:9], v[110:111], v[114:115]
	v_pk_fma_f32 v[84:85], v[10:11], v[112:113], v[116:117]
	v_pk_fma_f32 v[82:83], v[0:1], v[106:107], v[82:83]
	v_pk_fma_f32 v[84:85], v[2:3], v[108:109], v[84:85]
	v_pk_fma_f32 v[82:83], v[28:29], v[102:103], v[82:83]
	v_pk_fma_f32 v[84:85], v[30:31], v[104:105], v[84:85]
	v_pk_mul_f32 v[82:83], v[46:47], v[82:83]
	v_pk_mul_f32 v[84:85], v[42:43], v[84:85]
	v_pk_fma_f32 v[42:43], v[4:5], v[110:111], v[114:115]
	v_pk_fma_f32 v[46:47], v[6:7], v[112:113], v[116:117]
	v_pk_fma_f32 v[42:43], v[8:9], v[106:107], v[42:43]
	v_pk_fma_f32 v[46:47], v[10:11], v[108:109], v[46:47]
	v_pk_fma_f32 v[42:43], v[0:1], v[102:103], v[42:43]
	v_pk_fma_f32 v[46:47], v[2:3], v[104:105], v[46:47]
	v_pk_mul_f32 v[14:15], v[122:123], v[14:15]
	v_pk_mul_f32 v[12:13], v[124:125], v[12:13]
	v_pk_mul_f32 v[88:89], v[88:89], v[46:47]
	v_pk_mul_f32 v[86:87], v[86:87], v[42:43]
	v_cvt_pk_bf16_f32 v46, v14, v15
	v_cvt_pk_bf16_f32 v47, v38, v39
	v_cvt_pk_bf16_f32 v42, v12, v13
	v_cvt_pk_bf16_f32 v43, v34, v35
	v_cvt_pk_bf16_f32 v38, v82, v83
	v_cvt_pk_bf16_f32 v39, v84, v85
	s_nop 0
	v_cvt_pk_bf16_f32 v34, v86, v87
	v_cvt_pk_bf16_f32 v35, v88, v89
	s_and_saveexec_b64 s[8:9], s[0:1]
	s_cbranch_execz .LBB0_756
;     __device__ __forceinline__ void operator()(f32x4 (&acc)[2][2][4][2], const pg8::Unit& u, int wr, int wc, int fr, int fq) const {
;     ...
;             for (int m = 0; m < 4; ++m) if (fr != 0 || m >= 2) {
;                 u32x4 w; w.x = pk[0][m].x; w.y = pk[0][m].y; w.z = pk[1][m].x; w.w = pk[1][m].y;
;                 *(u32x4*)(ACT + (size_t)(tb + m) * DFF + colj) = w; }
	v_mov_b64_e32 v[12:13], s[22:23]
	v_mad_i64_i32 v[14:15], s[10:11], v66, s56, v[12:13]
	v_mad_i64_i32 v[12:13], s[10:11], v68, s56, v[12:13]
	v_lshl_add_u64 v[14:15], v[14:15], 0, v[64:65]
	v_lshl_add_u64 v[12:13], v[12:13], 0, v[64:65]
	global_store_dwordx4 v[14:15], v[44:47], off
	global_store_dwordx4 v[12:13], v[40:43], off
